# no start grid.sync; attention negm copy removed; P9 conv epilogue: early weight loads + hand-written masked-unpack/packed-gelu body
# speedup vs baseline: 1.0273x; 1.0273x over previous
.LBB0_5:
	s_or_b64 exec, exec, s[4:5]
	s_load_dwordx2 s[4:5], s[0:1], 0x100
	s_load_dwordx16 s[36:51], s[0:1], 0x0
	s_waitcnt lgkmcnt(0)
	v_writelane_b32 v236, s4, 5
	v_writelane_b32 v236, s5, 6

.LBB0_584:
	s_add_i32 s10, s65, -1
	s_and_b32 s67, s10, 1
	s_sub_i32 s10, s66, 63
	s_cmp_gt_i32 s10, s49
	s_cbranch_scc1 .LBB0_597
	s_mul_i32 s10, s67, 0x3000
	v_add_u32_e32 v52, s10, v129
	ds_read_b128 v[48:51], v52
	ds_read_b128 v[192:195], v52 offset:512
	ds_read_b128 v[196:199], v52 offset:2048
	ds_read_b128 v[200:203], v52 offset:2560
	ds_read_b128 v[204:207], v52 offset:4096
	ds_read_b128 v[208:211], v52 offset:4608
	ds_read_b128 v[212:215], v52 offset:6144
	ds_read_b128 v[216:219], v52 offset:6656
	ds_read_b128 v[220:223], v52 offset:8192
	ds_read_b128 v[224:227], v52 offset:8704
	ds_read_b128 v[228:231], v52 offset:10240
	ds_read_b128 v[232:235], v52 offset:10752
	s_setprio 1
	s_waitcnt lgkmcnt(11)
	v_mfma_f32_32x32x16_bf16 v[64:79], v[48:51], v[100:103], v[32:47]
	s_waitcnt lgkmcnt(9)
	v_mfma_f32_32x32x16_bf16 v[64:79], v[196:199], v[80:83], v[64:79]
	v_mfma_f32_32x32x16_bf16 v[48:63], v[192:195], v[100:103], v[32:47]
	s_waitcnt lgkmcnt(8)
	v_mfma_f32_32x32x16_bf16 v[48:63], v[200:203], v[80:83], v[48:63]
	s_waitcnt lgkmcnt(7)
	v_mfma_f32_32x32x16_bf16 v[64:79], v[204:207], v[84:87], v[64:79]
	s_waitcnt lgkmcnt(6)
	v_mfma_f32_32x32x16_bf16 v[48:63], v[208:211], v[84:87], v[48:63]
	s_waitcnt lgkmcnt(5)
	v_mfma_f32_32x32x16_bf16 v[64:79], v[212:215], v[88:91], v[64:79]
	s_waitcnt lgkmcnt(4)
	v_mfma_f32_32x32x16_bf16 v[48:63], v[216:219], v[88:91], v[48:63]
	s_waitcnt lgkmcnt(3)
	v_mfma_f32_32x32x16_bf16 v[64:79], v[220:223], v[92:95], v[64:79]
	s_waitcnt lgkmcnt(2)
	v_mfma_f32_32x32x16_bf16 v[48:63], v[224:227], v[92:95], v[48:63]
	s_waitcnt lgkmcnt(1)
	v_mfma_f32_32x32x16_bf16 v[64:79], v[228:231], v[96:99], v[64:79]
	s_waitcnt lgkmcnt(0)
	v_mfma_f32_32x32x16_bf16 v[48:63], v[232:235], v[96:99], v[48:63]
	s_setprio 0
	s_cmp_le_i32 s66, s63
	s_cbranch_scc1 .LBB0_587
	v_add_u32_e32 v143, s66, v126
	v_subrev_u32_e32 v147, 31, v143
	v_subrev_u32_e32 v145, 63, v143
	v_cmp_le_i32_e32 vcc, v147, v182
	s_nop 4
	v_cndmask_b32_e32 v48, v135, v48, vcc
	v_cmp_lt_i32_e32 vcc, v145, v182
	s_nop 1
	v_cndmask_b32_e32 v65, v135, v65, vcc
	v_cmp_le_i32_e32 vcc, v145, v182
	v_subrev_u32_e32 v145, 30, v143
	s_nop 0
	v_cndmask_b32_e32 v64, v135, v64, vcc
	v_cmp_le_i32_e32 vcc, v145, v182
	v_subrev_u32_e32 v145, 61, v143
	s_nop 0
	v_cndmask_b32_e32 v49, v135, v49, vcc
	v_cmp_le_i32_e32 vcc, v145, v182
	v_subrev_u32_e32 v145, 29, v143
	s_nop 0
	v_cndmask_b32_e32 v66, v135, v66, vcc
	v_cmp_le_i32_e32 vcc, v145, v182
	v_subrev_u32_e32 v145, 60, v143
	s_nop 0
	v_cndmask_b32_e32 v50, v135, v50, vcc
	v_cmp_le_i32_e32 vcc, v145, v182
	v_subrev_u32_e32 v145, 28, v143
	s_nop 0
	v_cndmask_b32_e32 v67, v135, v67, vcc
	v_cmp_le_i32_e32 vcc, v145, v182
	v_subrev_u32_e32 v145, 55, v143
	s_nop 0
	v_cndmask_b32_e32 v51, v135, v51, vcc
	v_cmp_le_i32_e32 vcc, v145, v182
	v_subrev_u32_e32 v145, 23, v143
	s_nop 0
	v_cndmask_b32_e32 v68, v135, v68, vcc
	v_cmp_le_i32_e32 vcc, v145, v182
	v_subrev_u32_e32 v145, 54, v143
	s_nop 0
	v_cndmask_b32_e32 v52, v135, v52, vcc
	v_cmp_le_i32_e32 vcc, v145, v182
	v_subrev_u32_e32 v145, 22, v143
	s_nop 0
	v_cndmask_b32_e32 v69, v135, v69, vcc
	v_cmp_le_i32_e32 vcc, v145, v182
	v_subrev_u32_e32 v145, 53, v143
	s_nop 0
	v_cndmask_b32_e32 v53, v135, v53, vcc
	v_cmp_le_i32_e32 vcc, v145, v182
	v_subrev_u32_e32 v145, 21, v143
	s_nop 0
	v_cndmask_b32_e32 v70, v135, v70, vcc
	v_cmp_le_i32_e32 vcc, v145, v182
	v_subrev_u32_e32 v145, 52, v143
	s_nop 0
	v_cndmask_b32_e32 v54, v135, v54, vcc
	v_cmp_le_i32_e32 vcc, v145, v182
	v_subrev_u32_e32 v145, 20, v143
	s_nop 0
	v_cndmask_b32_e32 v71, v135, v71, vcc
	v_cmp_le_i32_e32 vcc, v145, v182
	v_subrev_u32_e32 v145, 47, v143
	s_nop 0
	v_cndmask_b32_e32 v55, v135, v55, vcc
	v_cmp_le_i32_e32 vcc, v145, v182
	v_add_u32_e32 v145, -15, v143
	s_nop 0
	v_cndmask_b32_e32 v72, v135, v72, vcc
	v_cmp_le_i32_e32 vcc, v145, v182
	v_subrev_u32_e32 v145, 46, v143
	s_nop 0
	v_cndmask_b32_e32 v56, v135, v56, vcc
	v_cmp_le_i32_e32 vcc, v145, v182
	v_add_u32_e32 v145, -14, v143
	s_nop 0
	v_cndmask_b32_e32 v73, v135, v73, vcc
	v_cmp_le_i32_e32 vcc, v145, v182
	v_subrev_u32_e32 v145, 45, v143
	s_nop 0
	v_cndmask_b32_e32 v57, v135, v57, vcc
	v_cmp_le_i32_e32 vcc, v145, v182
	v_add_u32_e32 v145, -13, v143
	s_nop 0
	v_cndmask_b32_e32 v74, v135, v74, vcc
	v_cmp_le_i32_e32 vcc, v145, v182
	v_subrev_u32_e32 v145, 44, v143
	s_nop 0
	v_cndmask_b32_e32 v58, v135, v58, vcc
	v_cmp_le_i32_e32 vcc, v145, v182
	v_add_u32_e32 v145, -12, v143
	s_nop 0
	v_cndmask_b32_e32 v75, v135, v75, vcc
	v_cmp_le_i32_e32 vcc, v145, v182
	v_subrev_u32_e32 v145, 39, v143
	s_nop 0
	v_cndmask_b32_e32 v59, v135, v59, vcc
	v_cmp_le_i32_e32 vcc, v145, v182
	v_add_u32_e32 v145, -7, v143
	s_nop 0
	v_cndmask_b32_e32 v76, v135, v76, vcc
	v_cmp_le_i32_e32 vcc, v145, v182
	v_subrev_u32_e32 v145, 38, v143
	s_nop 0
	v_cndmask_b32_e32 v60, v135, v60, vcc
	v_cmp_le_i32_e32 vcc, v145, v182
	v_add_u32_e32 v145, -6, v143
	s_nop 0
	v_cndmask_b32_e32 v77, v135, v77, vcc
	v_cmp_le_i32_e32 vcc, v145, v182
	v_subrev_u32_e32 v145, 37, v143
	s_nop 0
	v_cndmask_b32_e32 v61, v135, v61, vcc
	v_cmp_le_i32_e32 vcc, v145, v182
	v_add_u32_e32 v145, -5, v143
	s_nop 0
	v_cndmask_b32_e32 v78, v135, v78, vcc
	v_cmp_le_i32_e32 vcc, v145, v182
	v_subrev_u32_e32 v145, 36, v143
	v_add_u32_e32 v143, -4, v143
	v_cndmask_b32_e32 v62, v135, v62, vcc
	v_cmp_le_i32_e32 vcc, v145, v182
	s_nop 1
	v_cndmask_b32_e32 v79, v135, v79, vcc
	v_cmp_le_i32_e32 vcc, v143, v182
	s_nop 1
	v_cndmask_b32_e32 v63, v135, v63, vcc

.LBB0_616:
	s_add_i32 s10, s63, -1
	s_and_b32 s65, s10, 1
	s_sub_i32 s10, s64, 63
	s_cmp_gt_i32 s10, s51
	s_cbranch_scc1 .LBB0_629
	s_mul_i32 s10, s65, 0x3000
	v_add_u32_e32 v52, s10, v129
	ds_read_b128 v[48:51], v52
	ds_read_b128 v[176:179], v52 offset:512
	ds_read_b128 v[184:187], v52 offset:2048
	ds_read_b128 v[192:195], v52 offset:2560
	ds_read_b128 v[196:199], v52 offset:4096
	ds_read_b128 v[200:203], v52 offset:4608
	ds_read_b128 v[204:207], v52 offset:6144
	ds_read_b128 v[208:211], v52 offset:6656
	ds_read_b128 v[212:215], v52 offset:8192
	ds_read_b128 v[216:219], v52 offset:8704
	ds_read_b128 v[220:223], v52 offset:10240
	ds_read_b128 v[224:227], v52 offset:10752
	s_setprio 1
	s_waitcnt lgkmcnt(11)
	v_mfma_f32_32x32x16_bf16 v[64:79], v[48:51], v[100:103], v[32:47]
	s_waitcnt lgkmcnt(9)
	v_mfma_f32_32x32x16_bf16 v[64:79], v[184:187], v[80:83], v[64:79]
	v_mfma_f32_32x32x16_bf16 v[48:63], v[176:179], v[100:103], v[32:47]
	s_waitcnt lgkmcnt(8)
	v_mfma_f32_32x32x16_bf16 v[48:63], v[192:195], v[80:83], v[48:63]
	s_waitcnt lgkmcnt(7)
	v_mfma_f32_32x32x16_bf16 v[64:79], v[196:199], v[84:87], v[64:79]
	s_waitcnt lgkmcnt(6)
	v_mfma_f32_32x32x16_bf16 v[48:63], v[200:203], v[84:87], v[48:63]
	s_waitcnt lgkmcnt(5)
	v_mfma_f32_32x32x16_bf16 v[64:79], v[204:207], v[88:91], v[64:79]
	s_waitcnt lgkmcnt(4)
	v_mfma_f32_32x32x16_bf16 v[48:63], v[208:211], v[88:91], v[48:63]
	s_waitcnt lgkmcnt(3)
	v_mfma_f32_32x32x16_bf16 v[64:79], v[212:215], v[92:95], v[64:79]
	s_waitcnt lgkmcnt(2)
	v_mfma_f32_32x32x16_bf16 v[48:63], v[216:219], v[92:95], v[48:63]
	s_waitcnt lgkmcnt(1)
	v_mfma_f32_32x32x16_bf16 v[64:79], v[220:223], v[96:99], v[64:79]
	s_waitcnt lgkmcnt(0)
	v_mfma_f32_32x32x16_bf16 v[48:63], v[224:227], v[96:99], v[48:63]
	s_setprio 0
	s_cmp_le_i32 s64, s47
	s_cbranch_scc1 .LBB0_619
	v_add_u32_e32 v145, s64, v126
	v_subrev_u32_e32 v149, 31, v145
	v_subrev_u32_e32 v147, 63, v145
	v_cmp_le_i32_e32 vcc, v149, v182
	s_nop 4
	v_cndmask_b32_e32 v48, v135, v48, vcc
	v_cmp_lt_i32_e32 vcc, v147, v182
	s_nop 1
	v_cndmask_b32_e32 v65, v135, v65, vcc
	v_cmp_le_i32_e32 vcc, v147, v182
	v_subrev_u32_e32 v147, 30, v145
	s_nop 0
	v_cndmask_b32_e32 v64, v135, v64, vcc
	v_cmp_le_i32_e32 vcc, v147, v182
	v_subrev_u32_e32 v147, 61, v145
	s_nop 0
	v_cndmask_b32_e32 v49, v135, v49, vcc
	v_cmp_le_i32_e32 vcc, v147, v182
	v_subrev_u32_e32 v147, 29, v145
	s_nop 0
	v_cndmask_b32_e32 v66, v135, v66, vcc
	v_cmp_le_i32_e32 vcc, v147, v182
	v_subrev_u32_e32 v147, 60, v145
	s_nop 0
	v_cndmask_b32_e32 v50, v135, v50, vcc
	v_cmp_le_i32_e32 vcc, v147, v182
	v_subrev_u32_e32 v147, 28, v145
	s_nop 0
	v_cndmask_b32_e32 v67, v135, v67, vcc
	v_cmp_le_i32_e32 vcc, v147, v182
	v_subrev_u32_e32 v147, 55, v145
	s_nop 0
	v_cndmask_b32_e32 v51, v135, v51, vcc
	v_cmp_le_i32_e32 vcc, v147, v182
	v_subrev_u32_e32 v147, 23, v145
	s_nop 0
	v_cndmask_b32_e32 v68, v135, v68, vcc
	v_cmp_le_i32_e32 vcc, v147, v182
	v_subrev_u32_e32 v147, 54, v145
	s_nop 0
	v_cndmask_b32_e32 v52, v135, v52, vcc
	v_cmp_le_i32_e32 vcc, v147, v182
	v_subrev_u32_e32 v147, 22, v145
	s_nop 0
	v_cndmask_b32_e32 v69, v135, v69, vcc
	v_cmp_le_i32_e32 vcc, v147, v182
	v_subrev_u32_e32 v147, 53, v145
	s_nop 0
	v_cndmask_b32_e32 v53, v135, v53, vcc
	v_cmp_le_i32_e32 vcc, v147, v182
	v_subrev_u32_e32 v147, 21, v145
	s_nop 0
	v_cndmask_b32_e32 v70, v135, v70, vcc
	v_cmp_le_i32_e32 vcc, v147, v182
	v_subrev_u32_e32 v147, 52, v145
	s_nop 0
	v_cndmask_b32_e32 v54, v135, v54, vcc
	v_cmp_le_i32_e32 vcc, v147, v182
	v_subrev_u32_e32 v147, 20, v145
	s_nop 0
	v_cndmask_b32_e32 v71, v135, v71, vcc
	v_cmp_le_i32_e32 vcc, v147, v182
	v_subrev_u32_e32 v147, 47, v145
	s_nop 0
	v_cndmask_b32_e32 v55, v135, v55, vcc
	v_cmp_le_i32_e32 vcc, v147, v182
	v_add_u32_e32 v147, -15, v145
	s_nop 0
	v_cndmask_b32_e32 v72, v135, v72, vcc
	v_cmp_le_i32_e32 vcc, v147, v182
	v_subrev_u32_e32 v147, 46, v145
	s_nop 0
	v_cndmask_b32_e32 v56, v135, v56, vcc
	v_cmp_le_i32_e32 vcc, v147, v182
	v_add_u32_e32 v147, -14, v145
	s_nop 0
	v_cndmask_b32_e32 v73, v135, v73, vcc
	v_cmp_le_i32_e32 vcc, v147, v182
	v_subrev_u32_e32 v147, 45, v145
	s_nop 0
	v_cndmask_b32_e32 v57, v135, v57, vcc
	v_cmp_le_i32_e32 vcc, v147, v182
	v_add_u32_e32 v147, -13, v145
	s_nop 0
	v_cndmask_b32_e32 v74, v135, v74, vcc
	v_cmp_le_i32_e32 vcc, v147, v182
	v_subrev_u32_e32 v147, 44, v145
	s_nop 0
	v_cndmask_b32_e32 v58, v135, v58, vcc
	v_cmp_le_i32_e32 vcc, v147, v182
	v_add_u32_e32 v147, -12, v145
	s_nop 0
	v_cndmask_b32_e32 v75, v135, v75, vcc
	v_cmp_le_i32_e32 vcc, v147, v182
	v_subrev_u32_e32 v147, 39, v145
	s_nop 0
	v_cndmask_b32_e32 v59, v135, v59, vcc
	v_cmp_le_i32_e32 vcc, v147, v182
	v_add_u32_e32 v147, -7, v145
	s_nop 0
	v_cndmask_b32_e32 v76, v135, v76, vcc
	v_cmp_le_i32_e32 vcc, v147, v182
	v_subrev_u32_e32 v147, 38, v145
	s_nop 0
	v_cndmask_b32_e32 v60, v135, v60, vcc
	v_cmp_le_i32_e32 vcc, v147, v182
	v_add_u32_e32 v147, -6, v145
	s_nop 0
	v_cndmask_b32_e32 v77, v135, v77, vcc
	v_cmp_le_i32_e32 vcc, v147, v182
	v_subrev_u32_e32 v147, 37, v145
	s_nop 0
	v_cndmask_b32_e32 v61, v135, v61, vcc
	v_cmp_le_i32_e32 vcc, v147, v182
	v_add_u32_e32 v147, -5, v145
	s_nop 0
	v_cndmask_b32_e32 v78, v135, v78, vcc
	v_cmp_le_i32_e32 vcc, v147, v182
	v_subrev_u32_e32 v147, 36, v145
	v_add_u32_e32 v145, -4, v145
	v_cndmask_b32_e32 v62, v135, v62, vcc
	v_cmp_le_i32_e32 vcc, v147, v182
	s_nop 1
	v_cndmask_b32_e32 v79, v135, v79, vcc
	v_cmp_le_i32_e32 vcc, v145, v182
	s_nop 1
	v_cndmask_b32_e32 v63, v135, v63, vcc

.LBB0_1036:
	v_mov_b32_e32 v130, v191
	s_waitcnt vmcnt(0)
	s_barrier
	v_lshl_or_b32 v216, s0, 7, v142
	v_lshlrev_b32_e32 v216, 2, v216
	v_add_u32_e32 v217, 0x2c00, v216
	global_load_dwordx4 v[148:151], v216, s[16:17]
	global_load_dwordx4 v[152:155], v216, s[16:17] offset:16
	global_load_dwordx4 v[180:183], v217, s[16:17]
	global_load_dwordx4 v[184:187], v217, s[16:17] offset:16
	global_load_dwordx4 v[156:159], v216, s[8:9]
	global_load_dwordx4 v[160:163], v216, s[8:9] offset:16
	global_load_dwordx4 v[192:195], v217, s[8:9]
	global_load_dwordx4 v[196:199], v217, s[8:9] offset:16
	global_load_dwordx4 v[164:167], v216, s[20:21]
	global_load_dwordx4 v[168:171], v216, s[20:21] offset:16
	global_load_dwordx4 v[200:203], v217, s[20:21]
	global_load_dwordx4 v[204:207], v217, s[20:21] offset:16
	global_load_dwordx4 v[172:175], v216, s[18:19]
	global_load_dwordx4 v[176:179], v216, s[18:19] offset:16
	global_load_dwordx4 v[208:211], v217, s[18:19]
	global_load_dwordx4 v[212:215], v217, s[18:19] offset:16
	s_lshl_b32 s1, s1, 6
	v_and_or_b32 v132, v130, 15, s61
	v_and_b32_e32 v130, 48, v130
	s_add_i32 s1, s1, 0
	v_mul_lo_u32 v132, v132, s50
	v_add3_u32 v130, s1, v130, v132
	v_cvt_pk_bf16_f32 v68, v68, v69
	v_cvt_pk_bf16_f32 v69, v70, v71
	v_cvt_pk_bf16_f32 v70, v64, v65
	v_add_u32_e32 v64, 0x10800, v130
	v_cvt_pk_bf16_f32 v60, v60, v61
	v_cvt_pk_bf16_f32 v61, v62, v63
	v_cvt_pk_bf16_f32 v62, v56, v57
	v_cvt_pk_bf16_f32 v63, v58, v59
	ds_write_b128 v64, v[60:63]
	v_cvt_pk_bf16_f32 v52, v52, v53
	v_cvt_pk_bf16_f32 v53, v54, v55
	v_cvt_pk_bf16_f32 v54, v48, v49
	v_cvt_pk_bf16_f32 v55, v50, v51
	v_add_u32_e32 v48, 0x10900, v130
	v_cvt_pk_bf16_f32 v36, v36, v37
	v_cvt_pk_bf16_f32 v37, v38, v39
	v_cvt_pk_bf16_f32 v38, v32, v33
	v_cvt_pk_bf16_f32 v39, v34, v35
	v_add_u32_e32 v32, 0x12a00, v130
	v_cvt_pk_bf16_f32 v20, v20, v21
	v_cvt_pk_bf16_f32 v21, v22, v23
	v_cvt_pk_bf16_f32 v22, v16, v17
	v_cvt_pk_bf16_f32 v23, v18, v19
	v_add_u32_e32 v16, 0x14b00, v130
	v_lshl_or_b32 v64, s0, 7, v142
	v_cvt_pk_bf16_f32 v124, v124, v125
	v_cvt_pk_bf16_f32 v125, v126, v127
	v_cvt_pk_bf16_f32 v126, v120, v121
	v_cvt_pk_bf16_f32 v127, v122, v123
	v_cvt_pk_bf16_f32 v116, v116, v117
	v_cvt_pk_bf16_f32 v117, v118, v119
	v_cvt_pk_bf16_f32 v118, v112, v113
	v_cvt_pk_bf16_f32 v119, v114, v115
	v_cvt_pk_bf16_f32 v108, v108, v109
	v_cvt_pk_bf16_f32 v109, v110, v111
	v_cvt_pk_bf16_f32 v110, v104, v105
	v_cvt_pk_bf16_f32 v111, v106, v107
	v_cvt_pk_bf16_f32 v100, v100, v101
	v_cvt_pk_bf16_f32 v101, v102, v103
	v_cvt_pk_bf16_f32 v102, v96, v97
	v_cvt_pk_bf16_f32 v103, v98, v99
	v_cvt_pk_bf16_f32 v92, v92, v93
	v_cvt_pk_bf16_f32 v93, v94, v95
	v_cvt_pk_bf16_f32 v94, v88, v89
	v_cvt_pk_bf16_f32 v95, v90, v91
	v_cvt_pk_bf16_f32 v84, v84, v85
	v_cvt_pk_bf16_f32 v85, v86, v87
	v_cvt_pk_bf16_f32 v86, v80, v81
	v_cvt_pk_bf16_f32 v87, v82, v83
	v_cvt_pk_bf16_f32 v76, v76, v77
	v_cvt_pk_bf16_f32 v77, v78, v79
	v_cvt_pk_bf16_f32 v78, v72, v73
	v_cvt_pk_bf16_f32 v79, v74, v75
	v_cvt_pk_bf16_f32 v71, v66, v67
	ds_write_b128 v48, v[52:55]
	v_add_u32_e32 v48, 0x12900, v130
	v_cvt_pk_bf16_f32 v44, v44, v45
	v_cvt_pk_bf16_f32 v45, v46, v47
	v_cvt_pk_bf16_f32 v46, v40, v41
	v_cvt_pk_bf16_f32 v47, v42, v43
	ds_write_b128 v32, v[36:39]
	v_add_u32_e32 v32, 0x14a00, v130
	v_cvt_pk_bf16_f32 v28, v28, v29
	v_cvt_pk_bf16_f32 v29, v30, v31
	v_cvt_pk_bf16_f32 v30, v24, v25
	v_cvt_pk_bf16_f32 v31, v26, v27
	ds_write_b128 v16, v[20:23]
	v_add_u32_e32 v16, 0x16b00, v130
	v_cvt_pk_bf16_f32 v12, v12, v13
	v_cvt_pk_bf16_f32 v13, v14, v15
	v_cvt_pk_bf16_f32 v14, v8, v9
	v_cvt_pk_bf16_f32 v15, v10, v11
	v_cvt_pk_bf16_f32 v4, v4, v5
	v_cvt_pk_bf16_f32 v5, v6, v7
	v_cvt_pk_bf16_f32 v6, v0, v1
	v_cvt_pk_bf16_f32 v7, v2, v3
	v_add_u32_e32 v0, 0x16c00, v130
	v_ashrrev_i32_e32 v65, 31, v64
	ds_write_b128 v130, v[124:127]
	ds_write_b128 v130, v[116:119] offset:256
	ds_write_b128 v130, v[108:111] offset:8448
	ds_write_b128 v130, v[100:103] offset:8704
	ds_write_b128 v130, v[92:95] offset:16896
	ds_write_b128 v130, v[84:87] offset:17152
	ds_write_b128 v130, v[76:79] offset:25344
	ds_write_b128 v130, v[68:71] offset:25600
	ds_write_b128 v48, v[44:47]
	ds_write_b128 v32, v[28:31]
	ds_write_b128 v16, v[12:15]
	ds_write_b128 v0, v[4:7]
	s_waitcnt lgkmcnt(0)
	s_barrier
	s_mulk_i32 s57, 0xfe
	s_mulk_i32 s59, 0xfe
	s_sub_i32 s0, s57, s59
	s_mul_i32 s58, s58, 0xa6b0
	s_sub_i32 s10, s0, s58
	v_lshl_add_u64 v[64:65], v[64:65], 1, s[14:15]
	s_add_i32 s10, s10, -2
	s_movk_i32 s11, 0xfbe0
	v_mov_b32_e32 v66, v143
	v_mov_b32_e32 v98, 0xbdd2d3e7
	v_mov_b32_e32 v99, 0xbdd2d3e7
	v_mov_b32_e32 v100, 0xc0135761
	v_mov_b32_e32 v101, 0xc0135761
	s_waitcnt vmcnt(0)
	s_branch .LBB0_1038

.LBB0_1038:
	v_add_u32_e32 v67, s10, v66
	v_cmp_lt_u32_e32 vcc, 1, v66
	v_cmp_gt_i32_e64 s[0:1], s54, v67
	s_and_b64 s[4:5], vcc, s[0:1]
	s_and_saveexec_b64 s[0:1], s[4:5]
	s_cbranch_execz .LBB0_1037
	v_add_u32_e32 v88, s11, v144
	ds_read_b128 v[68:71], v88 offset:1056
	ds_read_b128 v[76:79], v88 offset:528
	ds_read_b128 v[84:87], v88
	ds_read_b128 v[72:75], v88 offset:1312
	ds_read_b128 v[80:83], v88 offset:784
	ds_read_b128 v[88:91], v88 offset:256
	v_and_b32_e32 v96, 0xfff, v67
	v_min_u32_e32 v92, 1, v96
	v_lshrrev_b32_e32 v94, 1, v96
	v_lshlrev_b32_e32 v92, 16, v92
	v_min_u32_e32 v94, 1, v94
	v_sub_u32_e32 v93, 0, v92
	v_lshlrev_b32_e32 v94, 16, v94
	v_sub_u32_e32 v95, 0, v94
	s_waitcnt lgkmcnt(3)
	v_lshlrev_b32_e32 v118, 16, v68
	v_and_b32_e32 v119, 0xffff0000, v68
	v_pk_fma_f32 v[102:103], v[164:165], v[118:119], v[172:173]
	v_lshlrev_b32_e32 v120, 16, v69
	v_and_b32_e32 v121, 0xffff0000, v69
	v_pk_fma_f32 v[104:105], v[166:167], v[120:121], v[174:175]
	v_lshlrev_b32_e32 v122, 16, v70
	v_and_b32_e32 v123, 0xffff0000, v70
	v_pk_fma_f32 v[106:107], v[168:169], v[122:123], v[176:177]
	v_lshlrev_b32_e32 v124, 16, v71
	v_and_b32_e32 v125, 0xffff0000, v71
	v_pk_fma_f32 v[108:109], v[170:171], v[124:125], v[178:179]
	v_mul_u32_u24_e32 v118, v76, v92
	v_and_b32_e32 v119, v93, v76
	v_pk_fma_f32 v[102:103], v[156:157], v[118:119], v[102:103]
	v_mul_u32_u24_e32 v120, v77, v92
	v_and_b32_e32 v121, v93, v77
	v_pk_fma_f32 v[104:105], v[158:159], v[120:121], v[104:105]
	v_mul_u32_u24_e32 v122, v78, v92
	v_and_b32_e32 v123, v93, v78
	v_pk_fma_f32 v[106:107], v[160:161], v[122:123], v[106:107]
	v_mul_u32_u24_e32 v124, v79, v92
	v_and_b32_e32 v125, v93, v79
	v_pk_fma_f32 v[108:109], v[162:163], v[124:125], v[108:109]
	v_mul_u32_u24_e32 v118, v84, v94
	v_and_b32_e32 v119, v95, v84
	v_pk_fma_f32 v[102:103], v[148:149], v[118:119], v[102:103]
	v_mul_u32_u24_e32 v120, v85, v94
	v_and_b32_e32 v121, v95, v85
	v_pk_fma_f32 v[104:105], v[150:151], v[120:121], v[104:105]
	v_mul_u32_u24_e32 v122, v86, v94
	v_and_b32_e32 v123, v95, v86
	v_pk_fma_f32 v[106:107], v[152:153], v[122:123], v[106:107]
	v_mul_u32_u24_e32 v124, v87, v94
	v_and_b32_e32 v125, v95, v87
	v_pk_fma_f32 v[108:109], v[154:155], v[124:125], v[108:109]
	v_pk_mul_f32 v[110:111], v[102:103], v[102:103]
	v_pk_mul_f32 v[112:113], v[104:105], v[104:105]
	v_pk_mul_f32 v[114:115], v[106:107], v[106:107]
	v_pk_mul_f32 v[116:117], v[108:109], v[108:109]
	v_pk_fma_f32 v[110:111], v[110:111], v[98:99], v[100:101]
	v_pk_fma_f32 v[112:113], v[112:113], v[98:99], v[100:101]
	v_pk_fma_f32 v[114:115], v[114:115], v[98:99], v[100:101]
	v_pk_fma_f32 v[116:117], v[116:117], v[98:99], v[100:101]
	v_pk_mul_f32 v[110:111], v[102:103], v[110:111]
	v_pk_mul_f32 v[112:113], v[104:105], v[112:113]
	v_pk_mul_f32 v[114:115], v[106:107], v[114:115]
	v_pk_mul_f32 v[116:117], v[108:109], v[116:117]
	v_exp_f32_e32 v110, v110
	v_exp_f32_e32 v111, v111
	v_exp_f32_e32 v112, v112
	v_exp_f32_e32 v113, v113
	v_exp_f32_e32 v114, v114
	v_exp_f32_e32 v115, v115
	v_exp_f32_e32 v116, v116
	v_exp_f32_e32 v117, v117
	s_waitcnt lgkmcnt(0)
	v_lshlrev_b32_e32 v118, 16, v72
	v_and_b32_e32 v119, 0xffff0000, v72
	v_pk_fma_f32 v[68:69], v[200:201], v[118:119], v[208:209]
	v_lshlrev_b32_e32 v120, 16, v73
	v_and_b32_e32 v121, 0xffff0000, v73
	v_pk_fma_f32 v[70:71], v[202:203], v[120:121], v[210:211]
	v_lshlrev_b32_e32 v122, 16, v74
	v_and_b32_e32 v123, 0xffff0000, v74
	v_pk_fma_f32 v[76:77], v[204:205], v[122:123], v[212:213]
	v_lshlrev_b32_e32 v124, 16, v75
	v_and_b32_e32 v125, 0xffff0000, v75
	v_pk_fma_f32 v[78:79], v[206:207], v[124:125], v[214:215]
	v_mul_u32_u24_e32 v118, v80, v92
	v_and_b32_e32 v119, v93, v80
	v_pk_fma_f32 v[68:69], v[192:193], v[118:119], v[68:69]
	v_mul_u32_u24_e32 v120, v81, v92
	v_and_b32_e32 v121, v93, v81
	v_pk_fma_f32 v[70:71], v[194:195], v[120:121], v[70:71]
	v_mul_u32_u24_e32 v122, v82, v92
	v_and_b32_e32 v123, v93, v82
	v_pk_fma_f32 v[76:77], v[196:197], v[122:123], v[76:77]
	v_mul_u32_u24_e32 v124, v83, v92
	v_and_b32_e32 v125, v93, v83
	v_pk_fma_f32 v[78:79], v[198:199], v[124:125], v[78:79]
	v_mul_u32_u24_e32 v118, v88, v94
	v_and_b32_e32 v119, v95, v88
	v_pk_fma_f32 v[68:69], v[180:181], v[118:119], v[68:69]
	v_mul_u32_u24_e32 v120, v89, v94
	v_and_b32_e32 v121, v95, v89
	v_pk_fma_f32 v[70:71], v[182:183], v[120:121], v[70:71]
	v_mul_u32_u24_e32 v122, v90, v94
	v_and_b32_e32 v123, v95, v90
	v_pk_fma_f32 v[76:77], v[184:185], v[122:123], v[76:77]
	v_mul_u32_u24_e32 v124, v91, v94
	v_and_b32_e32 v125, v95, v91
	v_pk_fma_f32 v[78:79], v[186:187], v[124:125], v[78:79]
	v_pk_add_f32 v[110:111], v[110:111], 1.0 op_sel_hi:[1,0]
	v_pk_add_f32 v[112:113], v[112:113], 1.0 op_sel_hi:[1,0]
	v_pk_add_f32 v[114:115], v[114:115], 1.0 op_sel_hi:[1,0]
	v_pk_add_f32 v[116:117], v[116:117], 1.0 op_sel_hi:[1,0]
	v_rcp_f32_e32 v110, v110
	v_rcp_f32_e32 v111, v111
	v_rcp_f32_e32 v112, v112
	v_rcp_f32_e32 v113, v113
	v_rcp_f32_e32 v114, v114
	v_rcp_f32_e32 v115, v115
	v_rcp_f32_e32 v116, v116
	v_rcp_f32_e32 v117, v117
	v_mad_i64_i32 v[96:97], s[4:5], v67, s56, v[64:65]
	v_pk_mul_f32 v[102:103], v[102:103], v[110:111]
	v_pk_mul_f32 v[104:105], v[104:105], v[112:113]
	v_pk_mul_f32 v[106:107], v[106:107], v[114:115]
	v_pk_mul_f32 v[108:109], v[108:109], v[116:117]
	v_pk_mul_f32 v[102:103], v[102:103], v[68:69]
	v_pk_mul_f32 v[104:105], v[104:105], v[70:71]
	v_pk_mul_f32 v[106:107], v[106:107], v[76:77]
	v_pk_mul_f32 v[108:109], v[108:109], v[78:79]
	v_cvt_pk_bf16_f32 v92, v102, v103
	v_cvt_pk_bf16_f32 v93, v104, v105
	v_cvt_pk_bf16_f32 v94, v106, v107
	v_cvt_pk_bf16_f32 v95, v108, v109
	global_store_dwordx4 v[96:97], v[92:95], off
	s_branch .LBB0_1037
